# v66 with every warm-up read landing in spare v243 (vgpr count 244) plus re-warm of the kernel's code by workgroups 0..7 in front of the late waits of P3, P6, P8 and at the top of P9
# speedup vs baseline: 1.0097x; 1.0011x over previous
_Z10fwd_kernel4Args:
	s_load_dwordx16 s[56:71], s[0:1], 0x0
	s_load_dwordx16 s[4:19], s[0:1], 0x40
	s_load_dwordx16 s[40:55], s[0:1], 0xc0
	s_load_dword s33, s[0:1], 0x100
	v_lshl_add_u32 v24, v0, 2, 0
	s_mov_b32 s38, s2
	s_waitcnt lgkmcnt(0)
	v_writelane_b32 v242, s4, 0
	v_mov_b32_e32 v1, v0
	v_readfirstlane_b32 s3, v0
	s_getpc_b64 s[98:99]
	v_writelane_b32 v242, s98, 62
	v_writelane_b32 v242, s99, 63
	v_lshlrev_b32_e32 v232, 7, v0
	global_load_dword v243, v232, s[98:99]
	v_add_u32_e32 v234, 0x10000, v232
	global_load_dword v243, v234, s[98:99]
	v_add_u32_e32 v234, 0x20000, v232
	v_cmp_gt_u32_e32 vcc, 0x170, v0
	s_and_saveexec_b64 s[100:101], vcc
	global_load_dword v243, v234, s[98:99]
	s_mov_b64 exec, s[100:101]
	v_writelane_b32 v242, s5, 1
	v_writelane_b32 v242, s6, 2
	v_writelane_b32 v242, s7, 3
	v_writelane_b32 v242, s8, 4
	v_writelane_b32 v242, s9, 5
	v_writelane_b32 v242, s10, 6
	v_writelane_b32 v242, s11, 7
	v_writelane_b32 v242, s12, 8
	v_writelane_b32 v242, s13, 9
	v_writelane_b32 v242, s14, 10
	v_writelane_b32 v242, s15, 11
	v_writelane_b32 v242, s16, 12
	v_writelane_b32 v242, s17, 13
	v_writelane_b32 v242, s18, 14
	v_writelane_b32 v242, s19, 15
	s_load_dwordx16 s[4:19], s[0:1], 0x80
	v_add_u32_e32 v2, 0x21800, v24
	v_mov_b32_e32 v3, 0
	s_waitcnt lgkmcnt(0)
	v_writelane_b32 v242, s4, 16
	s_nop 1
	v_writelane_b32 v242, s5, 17
	v_writelane_b32 v242, s6, 18
	v_writelane_b32 v242, s7, 19
	v_writelane_b32 v242, s8, 20
	v_writelane_b32 v242, s9, 21
	v_writelane_b32 v242, s10, 22
	v_writelane_b32 v242, s11, 23
	v_writelane_b32 v242, s12, 24
	v_writelane_b32 v242, s13, 25
	v_writelane_b32 v242, s14, 26
	v_writelane_b32 v242, s15, 27
	v_writelane_b32 v242, s16, 28
	v_writelane_b32 v242, s17, 29
	v_writelane_b32 v242, s18, 30
	v_writelane_b32 v242, s19, 31
	s_add_u32 s4, s0, 0x100
	s_addc_u32 s5, s1, 0
	v_writelane_b32 v242, s4, 32
	s_mov_b32 s0, 0
	s_mov_b32 s1, 1
	v_writelane_b32 v242, s5, 33
	s_mov_b64 s[4:5], 0
	s_mov_b32 s6, s0
	s_branch .LBB0_2

.LBB0_272:
	s_or_b64 exec, exec, s[6:7]
	s_add_u32 s92, s54, 0xa000000
	s_addc_u32 s93, s55, 0
	s_add_u32 s82, s54, 0x2400
	s_addc_u32 s83, s55, 0
	s_add_u32 s80, s54, 0xd000000
	v_mov_b32_e32 v130, v0
	s_addc_u32 s81, s55, 0
	s_waitcnt lgkmcnt(0)
	s_mov_b64 s[4:5], -1
	s_andn2_b64 vcc, exec, s[16:17]
	v_bfe_u32 v88, v130, 4, 2
	v_and_b32_e32 v135, 15, v130
	v_lshlrev_b32_e32 v89, 4, v130
	v_ashrrev_i32_e32 v1, 4, v130
	v_lshlrev_b32_e32 v141, 2, v130
	v_cmp_eq_u32_e64 s[34:35], 0, v130
	s_cbranch_vccnz .LBB0_279
	v_add_u32_e32 v4, 0x200, v130
	v_and_b32_e32 v66, 0xf0, v89
	v_ashrrev_i32_e32 v90, 4, v4
	v_add_u32_e32 v4, 0x400, v130
	s_add_i32 s0, 0, 0x11000
	v_and_b32_e32 v7, 12, v141
	v_ashrrev_i32_e32 v91, 4, v4
	v_add_u32_e32 v4, 0x600, v130
	v_add_u32_e32 v5, s0, v66
	v_lshlrev_b32_e32 v93, 1, v7
	v_sub_u32_e32 v7, 0xff, v1
	s_movk_i32 s0, 0x110
	v_ashrrev_i32_e32 v92, 4, v4
	v_add_u32_e32 v4, 0, v66
	v_cvt_f32_i32_e32 v94, v7
	v_mul_lo_u32 v7, v1, s0
	v_add_u32_e32 v96, v4, v7
	v_add_u32_e32 v97, v5, v7
	v_sub_u32_e32 v7, 0xff, v90
	v_cvt_f32_i32_e32 v98, v7
	v_mul_lo_u32 v7, v90, s0
	v_add_u32_e32 v100, v4, v7
	v_add_u32_e32 v101, v5, v7
	v_sub_u32_e32 v7, 0xff, v91
	v_cvt_f32_i32_e32 v102, v7
	v_mul_lo_u32 v7, v91, s0
	v_add_u32_e32 v104, v4, v7
	v_add_u32_e32 v105, v5, v7
	v_sub_u32_e32 v7, 0xff, v92
	v_cvt_f32_i32_e32 v106, v7
	v_mul_lo_u32 v7, v92, s0
	v_add_u32_e32 v108, v4, v7
	v_add_u32_e32 v109, v5, v7
	v_add_u32_e32 v4, 0x80, v1
	v_sub_u32_e32 v5, 0x7f, v1
	v_cvt_f32_i32_e32 v112, v5
	v_cvt_f32_i32_e32 v113, v4
	v_add_u32_e32 v4, 0x80, v90
	v_sub_u32_e32 v5, 0x7f, v90
	s_lshl_b32 s3, s38, 1
	v_cvt_f32_i32_e32 v114, v5
	v_cvt_f32_i32_e32 v115, v4
	v_add_u32_e32 v4, 0x80, v91
	v_sub_u32_e32 v5, 0x7f, v91
	s_add_i32 s36, s3, 0xfffffec0
	v_cvt_f32_i32_e32 v116, v5
	v_cvt_f32_i32_e32 v117, v4
	v_add_u32_e32 v4, 0x80, v92
	v_sub_u32_e32 v5, 0x7f, v92
	s_bfe_u32 s18, s38, 0x20002
	v_readlane_b32 s0, v242, 0
	v_bfe_u32 v6, v130, 2, 2
	v_cvt_f32_i32_e32 v95, v1
	v_cvt_f32_i32_e32 v99, v90
	v_cvt_f32_i32_e32 v103, v91
	v_cvt_f32_i32_e32 v107, v92
	v_cvt_f32_i32_e32 v118, v5
	v_cvt_f32_i32_e32 v119, v4
	s_lshl_b32 s16, s18, 2
	v_readlane_b32 s4, v242, 4
	v_mov_b32_e32 v67, 0
	v_lshl_or_b32 v6, v88, 3, v6
	v_lshlrev_b32_e32 v4, 7, v135
	v_readlane_b32 s5, v242, 5
	s_add_u32 s16, s4, s16
	s_mov_b32 s73, 0
	v_lshl_add_u64 v[2:3], s[68:69], 0, v[66:67]
	v_mul_u32_u24_e32 v110, 0x110, v6
	v_lshlrev_b32_e32 v6, 2, v88
	v_or_b32_e32 v8, 0x800, v4
	v_or_b32_e32 v10, 0x1000, v4
	v_or_b32_e32 v12, 0x1800, v4
	v_or_b32_e32 v14, 0x2000, v4
	v_or_b32_e32 v16, 0x2800, v4
	v_or_b32_e32 v18, 0x3000, v4
	v_or_b32_e32 v20, 0x3800, v4
	v_readlane_b32 s1, v242, 1
	v_readlane_b32 s10, v242, 10
	v_readlane_b32 s11, v242, 11
	s_addc_u32 s17, s5, 0
	s_lshl_b32 s72, s18, 8
	v_add3_u32 v111, 0, v93, v110
	v_lshl_add_u64 v[68:69], v[2:3], 0, s[72:73]
	s_mov_b64 s[18:19], -1
	s_mov_b32 s0, 0xbfb8aa3b
	s_mov_b32 s1, 0x42ce8ed0
	s_mov_b32 s10, 0xc2b17218
	s_mov_b32 s11, 0x7f800000
	s_mov_b32 s24, 0x3f2aaaab
	v_mov_b32_e32 v120, 0x3ecc95a3
	s_mov_b32 s25, 0x3f317218
	s_mov_b32 s26, 0x33800000
	s_movk_i32 s27, 0x1400
	s_mov_b32 s28, 0x8800
	v_lshlrev_b32_e32 v70, 1, v6
	v_lshlrev_b32_e32 v72, 1, v4
	v_lshlrev_b32_e32 v74, 1, v8
	v_lshlrev_b32_e32 v76, 1, v10
	v_lshlrev_b32_e32 v66, 1, v12
	v_lshlrev_b32_e32 v78, 1, v14
	v_lshlrev_b32_e32 v80, 1, v16
	v_lshlrev_b32_e32 v82, 1, v18
	v_lshlrev_b32_e32 v84, 1, v20
	v_mov_b32_e32 v121, 0x7f800000
	v_mov_b32_e32 v86, 0x3f317218
	v_mov_b32_e32 v71, v67
	v_mov_b32_e32 v73, v67
	v_mov_b32_e32 v75, v67
	v_mov_b32_e32 v77, v67
	s_mov_b32 s5, 0
	v_readlane_b32 s2, v242, 2
	v_readlane_b32 s3, v242, 3
	v_readlane_b32 s6, v242, 6
	v_readlane_b32 s7, v242, 7
	v_readlane_b32 s8, v242, 8
	v_readlane_b32 s9, v242, 9
	v_readlane_b32 s12, v242, 12
	v_readlane_b32 s13, v242, 13
	v_readlane_b32 s14, v242, 14
	v_readlane_b32 s15, v242, 15
	s_cmp_gt_u32 s38, 7
	s_cbranch_scc1 .Lw2a_skip
	v_readlane_b32 s100, v242, 62
	v_readlane_b32 s101, v242, 63
	v_lshlrev_b32_e32 v234, 7, v0
	v_add_u32_e32 v235, 0x10000, v234
	v_add_u32_e32 v236, 0x20000, v234
	v_min_u32_e32 v236, 0x2b780, v236
	s_nop 1
	global_load_dword v243, v234, s[100:101]
	global_load_dword v243, v235, s[100:101]
	global_load_dword v243, v236, s[100:101]
.Lw2a_skip:
	v_readfirstlane_b32 s98, v0
	s_cmp_gt_u32 s98, 63
	s_cbranch_scc1 .Lh2a_done
	s_getreg_b32 s98, hwreg(HW_REG_XCC_ID, 0, 4)
	s_lshl_b32 s98, s98, 8
	v_mov_b32_e32 v232, s98
	v_add_u32_e32 v232, 0x6400, v232
	s_mov_b32 s98, 0

.LBB0_279:
	s_and_b64 vcc, exec, s[4:5]
	s_cbranch_vccz .LBB0_291
	s_cmp_gt_u32 s38, 7
	s_cbranch_scc1 .Lw2b_skip
	v_readlane_b32 s100, v242, 62
	v_readlane_b32 s101, v242, 63
	v_lshlrev_b32_e32 v234, 7, v0
	v_add_u32_e32 v235, 0x10000, v234
	v_add_u32_e32 v236, 0x20000, v234
	v_min_u32_e32 v236, 0x2b780, v236
	s_nop 1
	global_load_dword v243, v234, s[100:101]
	global_load_dword v243, v235, s[100:101]
	global_load_dword v243, v236, s[100:101]

.Lh4b_main:
	v_lshlrev_b32_e32 v1, 4, v215
	v_add_u32_e32 v2, 0x2000, v1
	v_ashrrev_i32_e32 v3, 31, v2
	v_lshrrev_b32_e32 v3, 22, v3
	v_add_u32_e32 v3, v2, v3
	v_ashrrev_i32_e32 v10, 10, v3
	v_mul_i32_i24_e32 v3, 0x400, v10
	v_sub_u32_e32 v2, v2, v3
	v_lshrrev_b32_e32 v3, 4, v2
	v_bitop3_b32 v2, v3, v2, 32 bitop3:0x6c
	v_ashrrev_i32_e32 v3, 31, v2
	v_lshrrev_b32_e32 v3, 26, v3
	v_add_u32_e32 v3, v2, v3
	v_lshlrev_b32_e32 v4, 3, v10
	v_ashrrev_i32_e32 v11, 6, v3
	v_and_b32_e32 v4, -16, v4
	v_add_u32_e32 v4, v11, v4
	v_and_b32_e32 v5, 3, v11
	s_mov_b32 s0, 0x1fffe0
	v_lshrrev_b32_e32 v6, 2, v4
	v_lshlrev_b32_e32 v7, 1, v4
	v_and_b32_e32 v3, 0xc0, v3
	v_and_or_b32 v5, v4, s0, v5
	v_and_b32_e32 v6, 4, v6
	v_and_b32_e32 v7, 24, v7
	v_sub_u32_e32 v2, v2, v3
	v_mov_b32_e32 v3, 1
	v_or3_b32 v5, v5, v6, v7
	v_lshlrev_b32_e32 v6, 5, v10
	v_ashrrev_i16_sdwa v2, v3, sext(v2) dst_sel:DWORD dst_unused:UNUSED_PAD src0_sel:DWORD src1_sel:BYTE_0
	v_and_b32_e32 v6, 32, v6
	v_bfe_i32 v12, v2, 0, 16
	v_add_lshl_u32 v2, v6, v12, 1
	v_lshl_add_u32 v130, v5, 11, v2
	v_lshl_add_u32 v132, v4, 11, v2
	v_bfe_i32 v2, v215, 27, 1
	v_lshrrev_b32_e32 v2, 22, v2
	v_add_u32_e32 v2, v1, v2
	v_and_b32_e32 v2, 0xfffffc00, v2
	v_sub_u32_e32 v1, v1, v2
	v_lshrrev_b32_e32 v2, 4, v1
	v_ashrrev_i32_e32 v4, 31, v215
	v_bitop3_b32 v1, v2, v1, 32 bitop3:0x6c
	v_lshrrev_b32_e32 v4, 26, v4
	v_ashrrev_i32_e32 v2, 31, v1
	v_add_u32_e32 v4, v215, v4
	v_lshrrev_b32_e32 v2, 26, v2
	v_ashrrev_i32_e32 v14, 6, v4
	v_add_u32_e32 v2, v1, v2
	v_lshlrev_b32_e32 v4, 3, v14
	v_ashrrev_i32_e32 v13, 6, v2
	v_and_b32_e32 v4, -16, v4
	v_add_u32_e32 v4, v13, v4
	v_and_b32_e32 v5, 3, v13
	s_ashr_i32 s62, s38, 31
	v_and_or_b32 v5, v4, s0, v5
	s_lshr_b32 s0, s62, 29
	s_add_i32 s0, s38, s0
	s_ashr_i32 s34, s3, 6
	s_ashr_i32 s1, s0, 3
	s_and_b32 s0, s0, -8
	s_ashr_i32 s4, s3, 8
	s_lshl_b32 s37, s34, 10
	s_sub_i32 s0, s38, s0
	s_cmp_lt_i32 s0, 0
	s_cselect_b32 s5, 25, 24
	s_mul_i32 s0, s0, s5
	s_add_i32 s0, s0, s1
	s_mul_hi_i32 s1, s0, 0x2aaaaaab
	s_lshr_b32 s5, s1, 31
	s_ashr_i32 s1, s1, 2
	s_add_i32 s1, s1, s5
	s_mul_i32 s5, s1, 6
	s_mul_i32 s1, s1, 24
	s_sub_i32 s0, s0, s1
	s_bfe_i32 s1, s0, 0x80000
	s_mul_i32 s1, s1, 43
	s_bfe_u32 s6, s1, 0x1000f
	s_bfe_u32 s1, s1, 0x80008
	s_add_i32 s6, s1, s6
	s_mul_i32 s1, s6, 6
	s_sub_i32 s0, s0, s1
	s_sext_i32_i8 s0, s0
	v_lshrrev_b32_e32 v6, 2, v4
	v_lshlrev_b32_e32 v7, 1, v4
	v_and_b32_e32 v2, 0xc0, v2
	s_add_i32 s86, s5, s0
	v_and_b32_e32 v6, 4, v6
	v_and_b32_e32 v7, 24, v7
	v_sub_u32_e32 v1, v1, v2
	s_ashr_i32 s87, s86, 31
	s_bfe_i64 s[8:9], s[6:7], 0x80000
	v_or3_b32 v5, v5, v6, v7
	v_lshlrev_b32_e32 v6, 5, v14
	v_ashrrev_i16_sdwa v1, v3, sext(v1) dst_sel:DWORD dst_unused:UNUSED_PAD src0_sel:DWORD src1_sel:BYTE_0
	s_lshl_b64 s[0:1], s[86:87], 19
	s_lshl_b64 s[8:9], s[8:9], 19
	v_and_b32_e32 v6, 32, v6
	v_bfe_i32 v15, v1, 0, 16
	s_add_u32 s26, s70, s8
	v_add_lshl_u32 v1, v6, v15, 1
	s_addc_u32 s27, s71, s9
	s_add_i32 s63, s37, 0
	v_lshl_add_u32 v134, v5, 11, v1
	s_add_i32 m0, s63, 0x10000
	v_lshl_add_u32 v136, v4, 11, v1
	s_cmp_gt_u32 s38, 7
	s_cbranch_scc1 .Lw4a_skip
	v_readlane_b32 s100, v242, 62
	v_readlane_b32 s101, v242, 63
	v_lshlrev_b32_e32 v234, 7, v0
	v_add_u32_e32 v235, 0x10000, v234
	v_add_u32_e32 v236, 0x20000, v234
	v_min_u32_e32 v236, 0x2b780, v236
	s_nop 1
	global_load_dword v243, v234, s[100:101]
	global_load_dword v243, v235, s[100:101]
	global_load_dword v243, v236, s[100:101]

.Lh5b_main:
	v_lshlrev_b32_e32 v1, 4, v12
	v_add_u32_e32 v2, 0x2000, v1
	v_ashrrev_i32_e32 v3, 31, v2
	v_lshrrev_b32_e32 v3, 22, v3
	v_add_u32_e32 v3, v2, v3
	v_ashrrev_i32_e32 v10, 10, v3
	v_mul_i32_i24_e32 v3, 0x400, v10
	v_sub_u32_e32 v2, v2, v3
	v_lshrrev_b32_e32 v3, 4, v2
	v_bitop3_b32 v2, v3, v2, 32 bitop3:0x6c
	v_ashrrev_i32_e32 v3, 31, v2
	v_lshrrev_b32_e32 v3, 26, v3
	v_add_u32_e32 v3, v2, v3
	v_lshlrev_b32_e32 v4, 3, v10
	v_ashrrev_i32_e32 v11, 6, v3
	v_and_b32_e32 v4, -16, v4
	v_add_u32_e32 v4, v11, v4
	v_and_b32_e32 v5, 3, v11
	s_mov_b32 s0, 0x1fffe0
	v_lshrrev_b32_e32 v6, 2, v4
	v_lshlrev_b32_e32 v7, 1, v4
	v_and_b32_e32 v3, 0xc0, v3
	v_and_or_b32 v5, v4, s0, v5
	v_and_b32_e32 v6, 4, v6
	v_and_b32_e32 v7, 24, v7
	v_sub_u32_e32 v2, v2, v3
	v_mov_b32_e32 v3, 1
	v_or3_b32 v5, v5, v6, v7
	v_lshlrev_b32_e32 v6, 5, v10
	v_ashrrev_i16_sdwa v2, v3, sext(v2) dst_sel:DWORD dst_unused:UNUSED_PAD src0_sel:DWORD src1_sel:BYTE_0
	v_and_b32_e32 v6, 32, v6
	v_bfe_i32 v13, v2, 0, 16
	v_add_lshl_u32 v2, v6, v13, 1
	v_lshl_add_u32 v146, v5, 11, v2
	v_lshl_add_u32 v148, v4, 11, v2
	v_bfe_i32 v2, v12, 27, 1
	v_lshrrev_b32_e32 v2, 22, v2
	v_add_u32_e32 v2, v1, v2
	v_and_b32_e32 v2, 0xfffffc00, v2
	v_sub_u32_e32 v1, v1, v2
	v_lshrrev_b32_e32 v2, 4, v1
	v_ashrrev_i32_e32 v4, 31, v12
	v_bitop3_b32 v1, v2, v1, 32 bitop3:0x6c
	v_lshrrev_b32_e32 v4, 26, v4
	v_ashrrev_i32_e32 v2, 31, v1
	v_add_u32_e32 v4, v12, v4
	v_lshrrev_b32_e32 v2, 26, v2
	v_ashrrev_i32_e32 v15, 6, v4
	v_add_u32_e32 v2, v1, v2
	v_lshlrev_b32_e32 v4, 3, v15
	v_ashrrev_i32_e32 v14, 6, v2
	v_and_b32_e32 v4, -16, v4
	v_add_u32_e32 v4, v14, v4
	v_and_b32_e32 v5, 3, v14
	v_and_or_b32 v5, v4, s0, v5
	s_ashr_i32 s0, s38, 31
	s_lshr_b32 s1, s0, 29
	s_add_i32 s1, s38, s1
	s_ashr_i32 s7, s4, 6
	s_ashr_i32 s6, s1, 3
	s_and_b32 s1, s1, -8
	s_ashr_i32 s5, s4, 8
	s_lshl_b32 s3, s7, 10
	s_sub_i32 s14, s38, s1
	s_cmp_lt_i32 s14, 0
	s_movk_i32 s1, 0x61
	s_cselect_b32 s15, s1, 0x60
	s_mul_i32 s14, s14, s15
	s_add_i32 s14, s14, s6
	s_mul_hi_i32 s6, s14, 0x2aaaaaab
	s_lshr_b32 s15, s6, 31
	s_ashr_i32 s6, s6, 4
	s_add_i32 s6, s6, s15
	s_mul_i32 s15, s6, 6
	s_mulk_i32 s6, 0x60
	s_sub_i32 s14, s14, s6
	s_bfe_i32 s6, s14, 0x80000
	s_mul_i32 s6, s6, 43
	s_bfe_u32 s16, s6, 0x1000f
	s_bfe_u32 s6, s6, 0x80008
	s_add_i32 s6, s6, s16
	s_mul_i32 s16, s6, 6
	s_sub_i32 s14, s14, s16
	s_sext_i32_i8 s14, s14
	v_lshrrev_b32_e32 v6, 2, v4
	v_lshlrev_b32_e32 v7, 1, v4
	v_and_b32_e32 v2, 0xc0, v2
	s_add_i32 s40, s15, s14
	v_and_b32_e32 v6, 4, v6
	v_and_b32_e32 v7, 24, v7
	v_sub_u32_e32 v1, v1, v2
	s_ashr_i32 s41, s40, 31
	s_bfe_i64 s[16:17], s[6:7], 0x80000
	v_or3_b32 v5, v5, v6, v7
	v_lshlrev_b32_e32 v6, 5, v15
	v_ashrrev_i16_sdwa v1, v3, sext(v1) dst_sel:DWORD dst_unused:UNUSED_PAD src0_sel:DWORD src1_sel:BYTE_0
	s_lshl_b64 s[14:15], s[40:41], 19
	s_lshl_b64 s[16:17], s[16:17], 19
	v_and_b32_e32 v6, 32, v6
	v_bfe_i32 v16, v1, 0, 16
	s_add_u32 s56, s88, s16
	v_add_lshl_u32 v1, v6, v16, 1
	s_addc_u32 s57, s89, s17
	s_add_i32 s41, s3, 0
	v_lshl_add_u32 v150, v5, 11, v1
	s_add_i32 m0, s41, 0x10000
	v_lshl_add_u32 v152, v4, 11, v1
	s_cmp_gt_u32 s38, 7
	s_cbranch_scc1 .Lw5a_skip
	v_readlane_b32 s100, v242, 62
	v_readlane_b32 s101, v242, 63
	v_lshlrev_b32_e32 v228, 7, v0
	v_add_u32_e32 v229, 0x10000, v228
	v_add_u32_e32 v230, 0x20000, v228
	v_min_u32_e32 v230, 0x2b780, v230
	s_nop 1
	global_load_dword v243, v228, s[100:101]
	global_load_dword v243, v229, s[100:101]
	global_load_dword v243, v230, s[100:101]
.Lw5a_skip:
	v_readfirstlane_b32 s98, v0
	s_cmp_gt_u32 s98, 63
	s_cbranch_scc1 .Lh5a_done
	s_getreg_b32 s98, hwreg(HW_REG_XCC_ID, 0, 4)
	s_lshl_b32 s98, s98, 8
	v_mov_b32_e32 v226, s98
	v_add_u32_e32 v226, 0x6400, v226
	s_mov_b32 s98, 0

.LBB0_640:
	s_or_b64 exec, exec, s[6:7]
	v_readlane_b32 s0, v242, 38
	v_readlane_b32 s1, v242, 39
	s_waitcnt lgkmcnt(0)
	s_barrier
	s_and_b64 vcc, exec, s[0:1]
	v_readfirstlane_b32 s34, v0
	s_cmp_gt_u32 s38, 7
	s_cbranch_scc1 .Lw9_skip
	v_readlane_b32 s100, v242, 62
	v_readlane_b32 s101, v242, 63
	v_lshlrev_b32_e32 v228, 7, v0
	v_add_u32_e32 v229, 0x10000, v228
	v_add_u32_e32 v230, 0x20000, v228
	v_min_u32_e32 v230, 0x2b780, v230
	s_nop 1
	global_load_dword v243, v228, s[100:101]
	global_load_dword v243, v229, s[100:101]
	global_load_dword v243, v230, s[100:101]
.Lw9_skip:
	v_lshlrev_b32_e32 v1, 4, v0
	v_add_u32_e32 v2, 0x2000, v1
	v_ashrrev_i32_e32 v3, 31, v2
	v_lshrrev_b32_e32 v3, 22, v3
	v_add_u32_e32 v3, v2, v3
	v_ashrrev_i32_e32 v10, 10, v3
	v_mul_i32_i24_e32 v3, 0x400, v10
	v_sub_u32_e32 v2, v2, v3
	v_lshrrev_b32_e32 v3, 4, v2
	v_bitop3_b32 v2, v3, v2, 32 bitop3:0x6c
	v_ashrrev_i32_e32 v3, 31, v2
	v_lshrrev_b32_e32 v3, 26, v3
	v_add_u32_e32 v3, v2, v3
	v_lshlrev_b32_e32 v4, 3, v10
	v_ashrrev_i32_e32 v11, 6, v3
	v_and_b32_e32 v4, -16, v4
	v_add_u32_e32 v4, v11, v4
	v_and_b32_e32 v5, 3, v11
	s_mov_b32 s0, 0x7ffe0
	v_lshrrev_b32_e32 v6, 2, v4
	v_lshlrev_b32_e32 v7, 1, v4
	v_and_b32_e32 v3, 0xc0, v3
	v_and_or_b32 v5, v4, s0, v5
	v_and_b32_e32 v6, 4, v6
	v_and_b32_e32 v7, 24, v7
	v_sub_u32_e32 v2, v2, v3
	v_mov_b32_e32 v3, 1
	v_or3_b32 v5, v5, v6, v7
	v_lshlrev_b32_e32 v6, 5, v10
	v_ashrrev_i16_sdwa v2, v3, sext(v2) dst_sel:DWORD dst_unused:UNUSED_PAD src0_sel:DWORD src1_sel:BYTE_0
	v_and_b32_e32 v6, 32, v6
	v_bfe_i32 v12, v2, 0, 16
	v_add_lshl_u32 v2, v6, v12, 1
	v_lshl_add_u32 v122, v5, 13, v2
	v_lshl_add_u32 v124, v4, 13, v2
	v_add_u32_e32 v124, 0xfffe0000, v124
	v_bfe_i32 v2, v0, 27, 1
	v_lshrrev_b32_e32 v2, 22, v2
	v_add_u32_e32 v2, v1, v2
	v_and_b32_e32 v2, 0xfffffc00, v2
	v_sub_u32_e32 v1, v1, v2
	v_lshrrev_b32_e32 v2, 4, v1
	v_ashrrev_i32_e32 v4, 31, v0
	v_bitop3_b32 v1, v2, v1, 32 bitop3:0x6c
	v_lshrrev_b32_e32 v4, 26, v4
	v_ashrrev_i32_e32 v2, 31, v1
	v_add_u32_e32 v4, v0, v4
	v_lshrrev_b32_e32 v2, 26, v2
	v_ashrrev_i32_e32 v14, 6, v4
	v_add_u32_e32 v2, v1, v2
	v_lshlrev_b32_e32 v4, 3, v14
	v_ashrrev_i32_e32 v13, 6, v2
	v_and_b32_e32 v4, -16, v4
	v_add_u32_e32 v4, v13, v4
	v_and_b32_e32 v5, 3, v13
	s_ashr_i32 s36, s38, 31
	v_and_or_b32 v5, v4, s0, v5
	s_lshr_b32 s0, s36, 29
	s_add_i32 s0, s38, s0
	s_ashr_i32 s3, s34, 6
	s_ashr_i32 s1, s0, 3
	s_and_b32 s0, s0, -8
	s_ashr_i32 s11, s34, 8
	s_lshl_b32 s35, s3, 10
	s_sub_i32 s0, s38, s0
	s_cmp_lt_i32 s0, 0
	s_cselect_b32 s4, 25, 24
	s_mul_i32 s0, s0, s4
	s_add_i32 s0, s0, s1
	s_mul_hi_i32 s1, s0, 0x2aaaaaab
	s_lshr_b32 s4, s1, 31
	s_ashr_i32 s1, s1, 2
	s_add_i32 s1, s1, s4
	s_mul_i32 s4, s1, 6
	s_mul_i32 s1, s1, 24
	s_sub_i32 s1, s0, s1
	s_mul_i32 s0, s1, 43
	s_bfe_u32 s5, s0, 0x1000f
	s_bfe_u32 s0, s0, 0x80008
	s_add_i32 s0, s0, s5
	s_mul_i32 s5, s0, 6
	s_sub_i32 s1, s1, s5
	s_sext_i32_i8 s1, s1
	v_lshrrev_b32_e32 v6, 2, v4
	v_lshlrev_b32_e32 v7, 1, v4
	v_and_b32_e32 v2, 0xc0, v2
	s_add_i32 s6, s4, s1
	v_and_b32_e32 v6, 4, v6
	v_and_b32_e32 v7, 24, v7
	v_sub_u32_e32 v1, v1, v2
	s_lshr_b32 s1, s38, 3
	s_and_b32 s0, s1, 3
	s_lshr_b32 s1, s1, 2
	s_and_b32 s6, s38, 7
	s_lshl_b32 s6, s6, 3
	s_add_i32 s6, s6, s1
	s_ashr_i32 s7, s6, 31
	s_bfe_i64 s[14:15], s[0:1], 0x80000
	v_or3_b32 v5, v5, v6, v7
	v_lshlrev_b32_e32 v6, 5, v14
	v_ashrrev_i16_sdwa v1, v3, sext(v1) dst_sel:DWORD dst_unused:UNUSED_PAD src0_sel:DWORD src1_sel:BYTE_0
	s_mul_i32 s4, s6, 0x180000
	s_mov_b32 s5, 0
	s_lshl_b64 s[14:15], s[14:15], 21
	v_and_b32_e32 v6, 32, v6
	v_bfe_i32 v15, v1, 0, 16
	s_add_u32 s26, s86, s14
	v_add_lshl_u32 v1, v6, v15, 1
	s_addc_u32 s27, s87, s15
	s_add_i32 s37, s35, 0
	v_lshl_add_u32 v134, v5, 13, v1
	s_add_i32 m0, s37, 0x10000
	v_lshl_add_u32 v136, v4, 13, v1
	global_load_lds_dwordx4 v134, s[26:27]
	s_add_i32 m0, s37, 0x12000
	s_add_u32 s14, s26, 0x100000
	global_load_lds_dwordx4 v122, s[26:27]
	s_addc_u32 s15, s27, 0
	s_add_i32 m0, s37, 0x14000
	v_mov_b32_e32 v135, 0
	global_load_lds_dwordx4 v134, s[14:15]
	s_add_i32 m0, s37, 0x16000
	v_mov_b32_e32 v123, v135
	global_load_lds_dwordx4 v122, s[14:15]
	s_add_u32 s14, s68, s4
	s_addc_u32 s15, s69, s5
	s_add_i32 s41, s37, 0x2000
	s_mov_b32 m0, s37
	s_add_u32 s4, s14, 0xc0000
	global_load_lds_dwordx4 v136, s[14:15]
	s_mov_b32 m0, s41
	s_addc_u32 s5, s15, 0
	s_add_i32 s42, s37, 0x4000
	global_load_lds_dwordx4 v124, s[14:15]
	s_mov_b32 m0, s42
	s_add_i32 s43, s37, 0x6000
	global_load_lds_dwordx4 v136, s[4:5]
	s_mov_b32 m0, s43
	v_mov_b32_e32 v137, v135
	global_load_lds_dwordx4 v124, s[4:5]
	v_mov_b32_e32 v125, v135
	s_mov_b32 s44, 0
	v_lshl_add_u64 v[8:9], s[26:27], 0, v[134:135]
	v_lshl_add_u64 v[6:7], s[26:27], 0, v[122:123]
	v_lshl_add_u64 v[4:5], s[14:15], 0, v[136:137]
	s_cmp_lg_u32 s11, 1
	v_lshl_add_u64 v[2:3], s[14:15], 0, v[124:125]
	s_cbranch_scc1 .LBB0_643
	s_barrier

	.amdhsa_kernel _Z10fwd_kernel4Args
		.amdhsa_group_segment_fixed_size 0
		.amdhsa_private_segment_fixed_size 0
		.amdhsa_kernarg_size 512
		.amdhsa_user_sgpr_count 2
		.amdhsa_user_sgpr_dispatch_ptr 0
		.amdhsa_user_sgpr_queue_ptr 0
		.amdhsa_user_sgpr_kernarg_segment_ptr 1
		.amdhsa_user_sgpr_dispatch_id 0
		.amdhsa_user_sgpr_kernarg_preload_length 0
		.amdhsa_user_sgpr_kernarg_preload_offset 0
		.amdhsa_user_sgpr_private_segment_size 0
		.amdhsa_uses_dynamic_stack 0
		.amdhsa_enable_private_segment 0
		.amdhsa_system_sgpr_workgroup_id_x 1
		.amdhsa_system_sgpr_workgroup_id_y 0
		.amdhsa_system_sgpr_workgroup_id_z 0
		.amdhsa_system_sgpr_workgroup_info 0
		.amdhsa_system_vgpr_workitem_id 0
		.amdhsa_next_free_vgpr 244
		.amdhsa_next_free_sgpr 102
		.amdhsa_accum_offset 244
		.amdhsa_reserve_vcc 1
		.amdhsa_float_round_mode_32 0
		.amdhsa_float_round_mode_16_64 0
		.amdhsa_float_denorm_mode_32 3
		.amdhsa_float_denorm_mode_16_64 3
		.amdhsa_dx10_clamp 1
		.amdhsa_ieee_mode 1
		.amdhsa_fp16_overflow 0
		.amdhsa_tg_split 0
		.amdhsa_exception_fp_ieee_invalid_op 0
		.amdhsa_exception_fp_denorm_src 0
		.amdhsa_exception_fp_ieee_div_zero 0
		.amdhsa_exception_fp_ieee_overflow 0
		.amdhsa_exception_fp_ieee_underflow 0
		.amdhsa_exception_fp_ieee_inexact 0
		.amdhsa_exception_int_div_zero 0
	.end_amdhsa_kernel

amdhsa.kernels:
  - .agpr_count:     0
    .args:
      - .offset:         0
        .size:           256
        .value_kind:     by_value
      - .offset:         256
        .size:           4
        .value_kind:     hidden_block_count_x
      - .offset:         260
        .size:           4
        .value_kind:     hidden_block_count_y
      - .offset:         264
        .size:           4
        .value_kind:     hidden_block_count_z
      - .offset:         268
        .size:           2
        .value_kind:     hidden_group_size_x
      - .offset:         270
        .size:           2
        .value_kind:     hidden_group_size_y
      - .offset:         272
        .size:           2
        .value_kind:     hidden_group_size_z
      - .offset:         274
        .size:           2
        .value_kind:     hidden_remainder_x
      - .offset:         276
        .size:           2
        .value_kind:     hidden_remainder_y
      - .offset:         278
        .size:           2
        .value_kind:     hidden_remainder_z
      - .offset:         296
        .size:           8
        .value_kind:     hidden_global_offset_x
      - .offset:         304
        .size:           8
        .value_kind:     hidden_global_offset_y
      - .offset:         312
        .size:           8
        .value_kind:     hidden_global_offset_z
      - .offset:         320
        .size:           2
        .value_kind:     hidden_grid_dims
      - .offset:         376
        .size:           4
        .value_kind:     hidden_dynamic_lds_size
    .group_segment_fixed_size: 0
    .kernarg_segment_align: 8
    .kernarg_segment_size: 512
    .language:       OpenCL C
    .language_version:
      - 2
      - 0
    .max_flat_workgroup_size: 512
    .name:           _Z10fwd_kernel4Args
    .private_segment_fixed_size: 0
    .sgpr_count:     108
    .sgpr_spill_count: 42
    .symbol:         _Z10fwd_kernel4Args.kd
    .uniform_work_group_size: 1
    .uses_dynamic_stack: false
    .vgpr_count:     244
    .vgpr_spill_count: 0
    .wavefront_size: 64
